# qup and kvup: task index remapped so all column tiles of a 128-token block run on the same XCD (activation rows fetched into that L2 once)
# baseline (speedup 1.0000x reference)
; #define TASK_LOOP(t, nt, base) for (int t = (int)((blockIdx.x + gridDim.x - ((unsigned)(base) % gridDim.x)) % gridDim.x); t < (nt); t += gridDim.x)
; DI void phase_qup(const Prm& p, unsigned char* smem_raw, int l, int S, int& base) {
;     ...
;   TASK_LOOP(t, 3 * 128, base) {
;     const int tn = t % 3, tm = t / 3, n0 = tn * 128, m0 = tm * 128;
;     {
;       const int row = tid >> 2, qf = tid & 3;
;       const u16* src = p.dcq + (size_t)(m0 + row) * 384 + qf * 96;
.LBB0_2019:
	s_and_b32 s99, s31, 7
	s_mul_i32 s99, s99, 48
	s_lshr_b32 s98, s31, 8
	s_lshl_b32 s98, s98, 5
	s_add_i32 s99, s99, s98
	s_bfe_u32 s98, s31, 0x50003
	s_add_i32 s99, s99, s98
	s_mul_hi_i32 s56, s99, 0x55555556
	s_lshr_b32 s2, s56, 31
	s_add_i32 s56, s56, s2
	s_lshl_b32 s54, s56, 7
	v_add_u32_e32 v0, s54, v69
	v_mad_i64_i32 v[2:3], s[2:3], v0, s33, v[66:67]
	v_mov_b32_e32 v0, 0
	s_mov_b64 s[2:3], 0

; DI f32x16 mfma(bf16x8 a, bf16x8 b, f32x16 c) { return __builtin_amdgcn_mfma_f32_32x32x16_bf16(a, b, c, 0, 0, 0); }
; template <bool RFA, bool RFB, class LA, class LB, class EPI>
; DI void gemm_tile2s(u16* smem, int nk, LA la, LB lb, EPI epi) {
;   const int tid = tidx(), lane = tid & 63, wave = tid >> 6;
;   const int wm = wave >> 2, wn = wave & 3, lr = lane & 31, lh = lane >> 5;
;   u16* As = smem;
;   u16* Bs = smem + 2 * TILE_ELEMS;
;   f32x16 acc[2];
;   acc[0] = zero16(); acc[1] = zero16();
;   u32x4 ra0[2], rb0[2], ra1[2], rb1[2];
;   auto ld = [&](u32x4 (&ra)[2], u32x4 (&rb)[2], int kt) __attribute__((always_inline)) {
;     const int k0 = kt * 64;
; #pragma unroll
;     for (int i = 0; i < 2; ++i) { const int c = tid + NTH * i; ra[i] = la(A_ROW(c), k0 + A_KC(c) * 8); rb[i] = lb(B_ROW(c), k0 + B_KC(c) * 8); }
;   };
;   auto stl = [&](u32x4 (&ra)[2], u32x4 (&rb)[2], int buf) __attribute__((always_inline)) {
; #pragma unroll
;     for (int i = 0; i < 2; ++i) {
;       const int c = tid + NTH * i;
;       *(u32x4*)(As + buf * TILE_ELEMS + A_ROW(c) * LDT + A_KC(c) * 8) = ra[i];
;       *(u32x4*)(Bs + buf * TILE_ELEMS + B_ROW(c) * LDT + B_KC(c) * 8) = rb[i];
;     }
;   };
;   auto compute = [&](int buf) __attribute__((always_inline)) {
;     const u16* Ab = As + buf * TILE_ELEMS + (wm * 64 + lr) * LDT + lh * 8;
;     const u16* Bb = Bs + buf * TILE_ELEMS + (wn * 32 + lr) * LDT + lh * 8;
; #pragma unroll
;     for (int ks = 0; ks < 4; ++ks) {
;       const bf16x8 a0 = *(const bf16x8*)(Ab + ks * 16);
;       const bf16x8 a1 = *(const bf16x8*)(Ab + 32 * LDT + ks * 16);
;       const bf16x8 b = *(const bf16x8*)(Bb + ks * 16);
;       acc[0] = mfma(a0, b, acc[0]);
;       acc[1] = mfma(a1, b, acc[1]);
;     }
;   };
;   ld(ra0, rb0, 0);
;   if (nk > 1) ld(ra1, rb1, 1);
;   stl(ra0, rb0, 0);
;   if (nk > 2) ld(ra0, rb0, 2);
; DI void phase_qup(const Prm& p, unsigned char* smem_raw, int l, int S, int& base) {
;     ...
;     auto la = [&](int row, int k) __attribute__((always_inline)) {
;       const int g32 = row & ~31;
;       const bool pe = ((n0 + g32) % 96) == 64;
;       return *(const u32x4*)(W + (size_t)(n0 + g32 + (pe ? (row & 31) : perm_m(row & 31))) * 384 + k);
;     };
;     auto lb = [&](int row, int k) __attribute__((always_inline)) { return *(const u32x4*)(p.dcq + (size_t)(m0 + row) * 384 + k); };
.LBB0_2023:
	s_or_b64 exec, exec, s[2:3]
	s_mul_i32 s2, s56, 3
	v_mov_b32_e32 v23, v224
	s_sub_i32 s2, s99, s2
	s_waitcnt lgkmcnt(0)
	s_barrier
	s_lshl_b32 s55, s2, 7
	v_ashrrev_i32_e32 v24, 3, v23
	v_and_b32_e32 v22, 0xffffffe0, v24
	v_add_u32_e32 v27, s55, v22
	v_mul_hi_i32 v0, v27, s82
	v_lshrrev_b32_e32 v2, 31, v0
	v_lshrrev_b32_e32 v0, 4, v0
	v_add_u32_e32 v0, v0, v2
	v_mul_lo_u32 v0, v0, s86
	v_sub_u32_e32 v0, v27, v0
	v_cmp_eq_u32_e32 vcc, 64, v0
	v_cmp_ne_u32_e64 s[2:3], 64, v0
	v_lshlrev_b32_e32 v0, 2, v24
	v_lshrrev_b32_e32 v2, 1, v24
	v_bfe_u32 v28, v23, 3, 2
	v_and_b32_e32 v25, 16, v0
	v_and_b32_e32 v26, 12, v2
	s_and_saveexec_b64 s[4:5], s[2:3]
	s_xor_b64 s[4:5], exec, s[4:5]
	v_or3_b32 v0, v26, v28, v25
	s_or_saveexec_b64 s[4:5], s[4:5]
	v_bfe_u32 v29, v23, 3, 5
	s_xor_b64 exec, exec, s[4:5]
	v_bfe_u32 v0, v23, 3, 5
	s_or_b64 exec, exec, s[4:5]
	v_readlane_b32 s36, v253, 24
	v_lshlrev_b32_e32 v2, 3, v23
	v_readlane_b32 s46, v253, 34
	v_readlane_b32 s47, v253, 35
	v_and_b32_e32 v4, 56, v2
	v_add_u32_e32 v0, v0, v27
	v_mov_b64_e32 v[2:3], s[6:7]
	v_add_u32_e32 v8, s54, v24
	v_mov_b64_e32 v[6:7], s[46:47]
	v_mad_i64_i32 v[2:3], s[4:5], v0, s33, v[2:3]
	v_lshlrev_b32_e32 v0, 1, v4
	v_mad_i64_i32 v[70:71], s[4:5], v8, s33, v[6:7]
	v_lshl_add_u64 v[2:3], v[2:3], 0, v[0:1]
	v_lshl_add_u64 v[18:19], v[70:71], 0, v[0:1]
	global_load_dwordx4 v[2:5], v[2:3], off
	v_add_u32_e32 v42, 0x200, v23
	global_load_dwordx4 v[6:9], v[18:19], off
	v_ashrrev_i32_e32 v50, 3, v42
	v_and_b32_e32 v10, 0xffffffe0, v50
	v_add_u32_e32 v30, s55, v10
	v_mul_hi_i32 v10, v30, s82
	v_lshrrev_b32_e32 v11, 31, v10
	v_lshrrev_b32_e32 v10, 4, v10
	v_add_u32_e32 v10, v10, v11
	v_mul_lo_u32 v10, v10, s86
	v_sub_u32_e32 v10, v30, v10
	v_cmp_ne_u32_e64 s[4:5], 64, v10
	v_lshlrev_b32_e32 v10, 2, v50
	v_lshrrev_b32_e32 v11, 1, v50
	v_bfe_u32 v31, v42, 3, 2
	v_and_b32_e32 v32, 16, v10
	v_and_b32_e32 v58, 12, v11
	v_readlane_b32 s37, v253, 25
	v_readlane_b32 s38, v253, 26
	v_readlane_b32 s39, v253, 27
	v_readlane_b32 s40, v253, 28
	v_readlane_b32 s41, v253, 29
	v_readlane_b32 s42, v253, 30
	v_readlane_b32 s43, v253, 31
	v_readlane_b32 s44, v253, 32
	v_readlane_b32 s45, v253, 33
	v_readlane_b32 s48, v253, 36
	v_readlane_b32 s49, v253, 37
	v_readlane_b32 s50, v253, 38
	v_readlane_b32 s51, v253, 39
	s_and_saveexec_b64 s[52:53], s[4:5]
	s_xor_b64 s[52:53], exec, s[52:53]
	v_or3_b32 v10, v58, v31, v32
	s_or_saveexec_b64 s[52:53], s[52:53]
	v_bfe_u32 v33, v42, 3, 5
	s_xor_b64 exec, exec, s[52:53]
	v_bfe_u32 v10, v42, 3, 5
	s_or_b64 exec, exec, s[52:53]
	v_readlane_b32 s36, v253, 24
	v_readlane_b32 s46, v253, 34
	v_readlane_b32 s47, v253, 35
	v_add_u32_e32 v12, v10, v30
	v_mov_b64_e32 v[10:11], s[6:7]
	v_add_u32_e32 v16, s54, v50
	v_mov_b64_e32 v[14:15], s[46:47]
	v_mad_i64_i32 v[10:11], s[52:53], v12, s33, v[10:11]
	v_mad_i64_i32 v[72:73], s[52:53], v16, s33, v[14:15]
	v_lshl_add_u64 v[10:11], v[10:11], 0, v[0:1]
	v_lshl_add_u64 v[20:21], v[72:73], 0, v[0:1]
	global_load_dwordx4 v[10:13], v[10:11], off
	v_readlane_b32 s37, v253, 25
	global_load_dwordx4 v[14:17], v[20:21], off
	v_readlane_b32 s38, v253, 26
	v_readlane_b32 s39, v253, 27
	v_readlane_b32 s40, v253, 28
	v_readlane_b32 s41, v253, 29
	v_readlane_b32 s42, v253, 30
	v_readlane_b32 s43, v253, 31
	v_readlane_b32 s44, v253, 32
	v_readlane_b32 s45, v253, 33
	v_readlane_b32 s48, v253, 36
	v_readlane_b32 s49, v253, 37
	v_readlane_b32 s50, v253, 38
	v_readlane_b32 s51, v253, 39
	s_and_saveexec_b64 s[52:53], s[2:3]
	s_xor_b64 s[52:53], exec, s[52:53]
	v_or3_b32 v34, v26, v28, v25
	s_andn2_saveexec_b64 s[52:53], s[52:53]
	v_bfe_u32 v34, v23, 3, 5
	s_or_b64 exec, exec, s[52:53]
	v_add_u32_e32 v36, v34, v27
	v_mov_b64_e32 v[34:35], s[6:7]
	v_mad_i64_i32 v[34:35], s[52:53], v36, s33, v[34:35]
	v_lshl_add_u64 v[34:35], v[34:35], 0, v[0:1]
	global_load_dwordx4 v[34:37], v[34:35], off offset:128
	s_nop 0
	global_load_dwordx4 v[38:41], v[18:19], off offset:128
	s_and_saveexec_b64 s[52:53], s[4:5]
	s_xor_b64 s[52:53], exec, s[52:53]
	v_or3_b32 v43, v58, v31, v32
	s_andn2_saveexec_b64 s[52:53], s[52:53]
	v_bfe_u32 v43, v42, 3, 5
	s_or_b64 exec, exec, s[52:53]
	v_add_u32_e32 v44, v43, v30
	v_mov_b64_e32 v[42:43], s[6:7]
	v_mad_i64_i32 v[42:43], s[52:53], v44, s33, v[42:43]
	v_lshl_add_u64 v[42:43], v[42:43], 0, v[0:1]
	global_load_dwordx4 v[42:45], v[42:43], off offset:128
	s_nop 0
	global_load_dwordx4 v[46:49], v[20:21], off offset:128
	v_mad_u64_u32 v[74:75], s[52:53], v24, s70, v[0:1]
	v_mad_u64_u32 v[76:77], s[52:53], v50, s70, v[0:1]
	s_waitcnt vmcnt(7)
; template <bool RFA, bool RFB, class LA, class LB, class EPI>
; DI void gemm_tile2s(u16* smem, int nk, LA la, LB lb, EPI epi) {
;     ...
;   ld(ra0, rb0, 0);
;   if (nk > 1) ld(ra1, rb1, 1);
;   stl(ra0, rb0, 0);
;   if (nk > 2) ld(ra0, rb0, 2);
;   __syncthreads();
; DI void phase_qup(const Prm& p, unsigned char* smem_raw, int l, int S, int& base) {
;     ...
;     auto la = [&](int row, int k) __attribute__((always_inline)) {
;       const int g32 = row & ~31;
;       const bool pe = ((n0 + g32) % 96) == 64;
;       return *(const u32x4*)(W + (size_t)(n0 + g32 + (pe ? (row & 31) : perm_m(row & 31))) * 384 + k);
	ds_write_b128 v74, v[2:5]
	s_waitcnt vmcnt(6)
	ds_write_b128 v74, v[6:9] offset:36864
	s_waitcnt vmcnt(5)
	ds_write_b128 v76, v[10:13]
	s_waitcnt vmcnt(4)
	ds_write_b128 v76, v[14:17] offset:36864
	s_and_saveexec_b64 s[52:53], s[2:3]
	s_xor_b64 s[2:3], exec, s[52:53]
	v_or3_b32 v29, v26, v28, v25
	s_andn2_saveexec_b64 s[2:3], s[2:3]
	s_or_b64 exec, exec, s[2:3]
	v_add_u32_e32 v4, v29, v27
	v_mov_b64_e32 v[2:3], s[6:7]
	v_mad_i64_i32 v[2:3], s[2:3], v4, s33, v[2:3]
	v_lshl_add_u64 v[2:3], v[2:3], 0, v[0:1]
	global_load_dwordx4 v[50:53], v[2:3], off offset:256
	global_load_dwordx4 v[54:57], v[18:19], off offset:256
	s_and_saveexec_b64 s[2:3], s[4:5]
	s_xor_b64 s[2:3], exec, s[2:3]
	v_or3_b32 v33, v58, v31, v32
	s_andn2_saveexec_b64 s[2:3], s[2:3]
	s_or_b64 exec, exec, s[2:3]
	v_add_u32_e32 v4, v33, v30
	v_mov_b64_e32 v[2:3], s[6:7]
	v_mad_i64_i32 v[2:3], s[2:3], v4, s33, v[2:3]
	v_lshl_add_u64 v[2:3], v[2:3], 0, v[0:1]
	global_load_dwordx4 v[58:61], v[2:3], off offset:256
	global_load_dwordx4 v[62:65], v[20:21], off offset:256
	v_ashrrev_i32_e32 v2, 2, v23
	v_and_b32_e32 v0, 31, v23
	v_bfe_u32 v77, v23, 5, 1
	v_and_b32_e32 v75, 0xffffffc0, v2
	v_or_b32_e32 v2, v75, v0
	v_lshlrev_b32_e32 v68, 4, v77
	v_mad_u64_u32 v[78:79], s[2:3], v2, s70, v[68:69]
	v_lshrrev_b32_e32 v2, 1, v23
	v_and_or_b32 v79, v2, s86, v0
	v_mul_u32_u24_e32 v0, 0x48, v79
	v_lshl_add_u32 v87, v0, 1, v68
	v_and_b32_e32 v0, 3, v24
	v_or3_b32 v0, v26, v0, v25
	v_and_b32_e32 v2, 31, v24
	v_cndmask_b32_e32 v2, v0, v2, vcc
	v_lshl_or_b32 v2, s99, 7, v2
	v_readlane_b32 s2, v255, 7
	v_add_u32_e32 v2, v2, v22
	s_mulk_i32 s56, 0x180
	v_readlane_b32 s3, v255, 8
	v_subrev_u32_e32 v5, s56, v2
	v_and_b32_e32 v0, 7, v23
	v_mov_b64_e32 v[2:3], s[2:3]
	v_mad_i64_i32 v[80:81], s[2:3], v5, s33, v[2:3]
	v_mad_i64_i32 v[82:83], s[2:3], v4, s33, v[2:3]
	v_mov_b32_e32 v2, 0
	v_lshlrev_b32_e32 v0, 4, v0
	s_mov_b32 s4, -2
	v_mov_b32_e32 v3, v2
	v_mov_b32_e32 v4, v2
	v_mov_b32_e32 v5, v2
	v_mov_b32_e32 v6, v2
	v_mov_b32_e32 v7, v2
	v_mov_b32_e32 v8, v2
	v_mov_b32_e32 v9, v2
	v_mov_b32_e32 v10, v2
	v_mov_b32_e32 v11, v2
	v_mov_b32_e32 v12, v2
	v_mov_b32_e32 v13, v2
	v_mov_b32_e32 v14, v2
	v_mov_b32_e32 v15, v2
	v_mov_b32_e32 v16, v2
	v_mov_b32_e32 v17, v2
	v_mov_b32_e32 v18, v2
	v_mov_b32_e32 v19, v2
	v_mov_b32_e32 v20, v2
	v_mov_b32_e32 v21, v2
	v_mov_b32_e32 v22, v2
	v_mov_b32_e32 v23, v2
	v_mov_b32_e32 v24, v2
	v_mov_b32_e32 v25, v2
	v_mov_b32_e32 v26, v2
	v_mov_b32_e32 v27, v2
	v_mov_b32_e32 v28, v2
	v_mov_b32_e32 v29, v2
	v_mov_b32_e32 v30, v2
	v_mov_b32_e32 v31, v2
	v_mov_b32_e32 v32, v2
	v_mov_b32_e32 v33, v2
	s_waitcnt lgkmcnt(0)
	s_barrier
	s_branch .LBB0_2045

; #define TASK_LOOP(t, nt, base) for (int t = (int)((blockIdx.x + gridDim.x - ((unsigned)(base) % gridDim.x)) % gridDim.x); t < (nt); t += gridDim.x)
; DI void phase_kvup(const Prm& p, unsigned char* smem_raw, int l, int& base) {
;     ...
;   TASK_LOOP(t, 4 * 128, base) {
;     const int tn = t & 3, tm = t >> 2, n0 = tn * 128, m0 = tm * 128;
;     {
;       const int row = tid >> 2, qf = tid & 3;
;       const u16* src = p.dckv + (size_t)(m0 + row) * 320 + qf * 80;
;       float ss = 0.f;
.LBB0_2061:
	s_and_b32 s99, s31, 7
	s_lshl_b32 s99, s99, 6
	s_lshr_b32 s98, s31, 8
	s_lshl_b32 s98, s98, 5
	s_or_b32 s99, s99, s98
	s_bfe_u32 s98, s31, 0x50003
	s_or_b32 s99, s99, s98
	s_lshl_b32 s2, s99, 5
	s_and_b32 s2, s2, 0xffffff80
	s_ashr_i32 s3, s2, 31
	v_lshl_add_u64 v[4:5], v[80:81], 0, s[2:3]
	v_mad_u64_u32 v[2:3], s[2:3], v4, s65, v[82:83]
	v_mad_i32_i24 v3, v5, s65, v3
	v_mov_b32_e32 v0, 0
	s_mov_b64 s[2:3], 0

; DI f32x16 mfma(bf16x8 a, bf16x8 b, f32x16 c) { return __builtin_amdgcn_mfma_f32_32x32x16_bf16(a, b, c, 0, 0, 0); }
; template <bool RFA, bool RFB, class LA, class LB, class EPI>
; DI void gemm_tile2s(u16* smem, int nk, LA la, LB lb, EPI epi) {
;   const int tid = tidx(), lane = tid & 63, wave = tid >> 6;
;   const int wm = wave >> 2, wn = wave & 3, lr = lane & 31, lh = lane >> 5;
;   u16* As = smem;
;   u16* Bs = smem + 2 * TILE_ELEMS;
;   f32x16 acc[2];
;   acc[0] = zero16(); acc[1] = zero16();
;   u32x4 ra0[2], rb0[2], ra1[2], rb1[2];
;   auto ld = [&](u32x4 (&ra)[2], u32x4 (&rb)[2], int kt) __attribute__((always_inline)) {
;     const int k0 = kt * 64;
; #pragma unroll
;     for (int i = 0; i < 2; ++i) { const int c = tid + NTH * i; ra[i] = la(A_ROW(c), k0 + A_KC(c) * 8); rb[i] = lb(B_ROW(c), k0 + B_KC(c) * 8); }
;   };
;   auto stl = [&](u32x4 (&ra)[2], u32x4 (&rb)[2], int buf) __attribute__((always_inline)) {
; #pragma unroll
;     for (int i = 0; i < 2; ++i) {
;       const int c = tid + NTH * i;
;       *(u32x4*)(As + buf * TILE_ELEMS + A_ROW(c) * LDT + A_KC(c) * 8) = ra[i];
;       *(u32x4*)(Bs + buf * TILE_ELEMS + B_ROW(c) * LDT + B_KC(c) * 8) = rb[i];
;     }
;   };
;   auto compute = [&](int buf) __attribute__((always_inline)) {
;     const u16* Ab = As + buf * TILE_ELEMS + (wm * 64 + lr) * LDT + lh * 8;
;     const u16* Bb = Bs + buf * TILE_ELEMS + (wn * 32 + lr) * LDT + lh * 8;
; #pragma unroll
;     for (int ks = 0; ks < 4; ++ks) {
;       const bf16x8 a0 = *(const bf16x8*)(Ab + ks * 16);
;       const bf16x8 a1 = *(const bf16x8*)(Ab + 32 * LDT + ks * 16);
;       const bf16x8 b = *(const bf16x8*)(Bb + ks * 16);
;       acc[0] = mfma(a0, b, acc[0]);
;       acc[1] = mfma(a1, b, acc[1]);
;     }
;   };
;   ld(ra0, rb0, 0);
;   if (nk > 1) ld(ra1, rb1, 1);
;   stl(ra0, rb0, 0);
;   if (nk > 2) ld(ra0, rb0, 2);
;   __syncthreads();
; DI void phase_kvup(const Prm& p, unsigned char* smem_raw, int l, int& base) {
;     ...
;     const u16* W = p.WkvT + (size_t)l * 512 * 320;
;     auto la = [&](int row, int k) __attribute__((always_inline)) {
;       const int g32 = row & ~31;
;       return *(const u32x4*)(W + (size_t)(n0 + g32 + (g32 < 64 ? perm_m(row & 31) : (row & 31))) * 320 + k);
;     };
;     auto lb = [&](int row, int k) __attribute__((always_inline)) { return *(const u32x4*)(p.dckv + (size_t)(m0 + row) * 320 + k); };
.LBB0_2065:
	s_or_b64 exec, exec, s[2:3]
	v_mov_b32_e32 v19, v224
	s_waitcnt lgkmcnt(0)
	s_barrier
	s_nop 0
	v_ashrrev_i32_e32 v18, 3, v19
	v_and_b32_e32 v0, 0xffffffe0, v18
	v_cmp_gt_i32_e32 vcc, 64, v0
	v_cmp_lt_i32_e64 s[2:3], 63, v0
	v_bfe_u32 v23, v19, 3, 5
	s_and_saveexec_b64 s[4:5], s[2:3]
	s_xor_b64 s[4:5], exec, s[4:5]
	v_bfe_u32 v2, v19, 3, 5
	s_or_saveexec_b64 s[4:5], s[4:5]
	v_lshlrev_b32_e32 v3, 2, v18
	v_lshrrev_b32_e32 v4, 1, v18
	v_bfe_u32 v24, v19, 3, 2
	v_and_b32_e32 v20, 16, v3
	v_and_b32_e32 v21, 12, v4
	s_xor_b64 exec, exec, s[4:5]
	v_or3_b32 v2, v21, v24, v20
	s_or_b64 exec, exec, s[4:5]
	s_and_b32 s55, s99, 3
	s_lshl_b32 s57, s55, 7
	s_lshl_b32 s4, s99, 5
	v_readlane_b32 s36, v253, 24
	v_lshlrev_b32_e32 v3, 3, v19
	s_and_b32 s56, s4, 0xffffff80
	v_add_u32_e32 v22, s57, v0
	v_readlane_b32 s48, v253, 36
	v_readlane_b32 s49, v253, 37
	v_and_b32_e32 v4, 56, v3
	v_add_u32_e32 v0, v2, v22
	v_mov_b64_e32 v[2:3], s[6:7]
	v_add_u32_e32 v8, s56, v18
	v_mov_b64_e32 v[6:7], s[48:49]
	v_mad_i64_i32 v[2:3], s[4:5], v0, s65, v[2:3]
	v_lshlrev_b32_e32 v0, 1, v4
	v_mad_i64_i32 v[6:7], s[4:5], v8, s65, v[6:7]
	v_lshl_add_u64 v[2:3], v[2:3], 0, v[0:1]
	v_lshl_add_u64 v[86:87], v[6:7], 0, v[0:1]
	global_load_dwordx4 v[2:5], v[2:3], off
	v_add_u32_e32 v31, 0x200, v19
	global_load_dwordx4 v[6:9], v[86:87], off
	v_ashrrev_i32_e32 v30, 3, v31
	v_and_b32_e32 v10, 0xffffffe0, v30
	v_cmp_lt_i32_e64 s[4:5], 63, v10
	v_bfe_u32 v25, v31, 3, 5
	v_readlane_b32 s37, v253, 25
	v_readlane_b32 s38, v253, 26
	v_readlane_b32 s39, v253, 27
	v_readlane_b32 s40, v253, 28
	v_readlane_b32 s41, v253, 29
	v_readlane_b32 s42, v253, 30
	v_readlane_b32 s43, v253, 31
	v_readlane_b32 s44, v253, 32
	v_readlane_b32 s45, v253, 33
	v_readlane_b32 s46, v253, 34
	v_readlane_b32 s47, v253, 35
	v_readlane_b32 s50, v253, 38
	v_readlane_b32 s51, v253, 39
	s_and_saveexec_b64 s[52:53], s[4:5]
	s_xor_b64 s[52:53], exec, s[52:53]
	v_bfe_u32 v11, v31, 3, 5
	s_or_saveexec_b64 s[52:53], s[52:53]
	v_lshlrev_b32_e32 v12, 2, v30
	v_lshrrev_b32_e32 v13, 1, v30
	v_bfe_u32 v26, v31, 3, 2
	v_and_b32_e32 v27, 16, v12
	v_and_b32_e32 v29, 12, v13
	s_xor_b64 exec, exec, s[52:53]
	v_or3_b32 v11, v29, v26, v27
	s_or_b64 exec, exec, s[52:53]
	v_readlane_b32 s36, v253, 24
	v_add_u32_e32 v28, s57, v10
	v_readlane_b32 s48, v253, 36
	v_readlane_b32 s49, v253, 37
	v_add_u32_e32 v12, v11, v28
	v_mov_b64_e32 v[10:11], s[6:7]
	v_add_u32_e32 v16, s56, v30
	v_mov_b64_e32 v[14:15], s[48:49]
	v_mad_i64_i32 v[10:11], s[52:53], v12, s65, v[10:11]
	v_mad_i64_i32 v[14:15], s[52:53], v16, s65, v[14:15]
	v_lshl_add_u64 v[10:11], v[10:11], 0, v[0:1]
	v_lshl_add_u64 v[90:91], v[14:15], 0, v[0:1]
	global_load_dwordx4 v[10:13], v[10:11], off
	v_readlane_b32 s37, v253, 25
	global_load_dwordx4 v[14:17], v[90:91], off
	v_readlane_b32 s38, v253, 26
	v_readlane_b32 s39, v253, 27
	v_readlane_b32 s40, v253, 28
	v_readlane_b32 s41, v253, 29
	v_readlane_b32 s42, v253, 30
	v_readlane_b32 s43, v253, 31
	v_readlane_b32 s44, v253, 32
	v_readlane_b32 s45, v253, 33
	v_readlane_b32 s46, v253, 34
	v_readlane_b32 s47, v253, 35
	v_readlane_b32 s50, v253, 38
	v_readlane_b32 s51, v253, 39
	s_and_saveexec_b64 s[52:53], s[2:3]
	s_xor_b64 s[52:53], exec, s[52:53]
	v_bfe_u32 v32, v19, 3, 5
	s_andn2_saveexec_b64 s[52:53], s[52:53]
	v_or3_b32 v32, v21, v24, v20
	s_or_b64 exec, exec, s[52:53]
	v_add_u32_e32 v34, v32, v22
	v_mov_b64_e32 v[32:33], s[6:7]
	v_mad_i64_i32 v[32:33], s[52:53], v34, s65, v[32:33]
	v_lshl_add_u64 v[32:33], v[32:33], 0, v[0:1]
	global_load_dwordx4 v[48:51], v[32:33], off offset:128
	global_load_dwordx4 v[52:55], v[86:87], off offset:128
	s_and_saveexec_b64 s[52:53], s[4:5]
	s_xor_b64 s[52:53], exec, s[52:53]
	v_bfe_u32 v32, v31, 3, 5
	s_andn2_saveexec_b64 s[52:53], s[52:53]
	v_or3_b32 v32, v29, v26, v27
	s_or_b64 exec, exec, s[52:53]
	v_add_u32_e32 v31, v32, v28
	v_mov_b64_e32 v[32:33], s[6:7]
	v_mad_i64_i32 v[32:33], s[52:53], v31, s65, v[32:33]
	v_lshl_add_u64 v[32:33], v[32:33], 0, v[0:1]
	global_load_dwordx4 v[56:59], v[32:33], off offset:128
	global_load_dwordx4 v[60:63], v[90:91], off offset:128
	v_mad_u64_u32 v[92:93], s[52:53], v18, s70, v[0:1]
	v_mad_u64_u32 v[94:95], s[52:53], v30, s70, v[0:1]
	s_waitcnt vmcnt(7)
	ds_write_b128 v92, v[2:5]
	s_waitcnt vmcnt(6)
	ds_write_b128 v92, v[6:9] offset:36864
	s_waitcnt vmcnt(5)
	ds_write_b128 v94, v[10:13]
	s_waitcnt vmcnt(4)
	ds_write_b128 v94, v[14:17] offset:36864
	s_and_saveexec_b64 s[52:53], s[2:3]
	s_xor_b64 s[2:3], exec, s[52:53]
	s_andn2_saveexec_b64 s[2:3], s[2:3]
	v_or3_b32 v23, v21, v24, v20
	s_or_b64 exec, exec, s[2:3]
	v_add_u32_e32 v4, v23, v22
	v_mov_b64_e32 v[2:3], s[6:7]
	v_mad_i64_i32 v[2:3], s[2:3], v4, s65, v[2:3]
	v_lshl_add_u64 v[2:3], v[2:3], 0, v[0:1]
	global_load_dwordx4 v[64:67], v[2:3], off offset:256
	global_load_dwordx4 v[68:71], v[86:87], off offset:256
	s_and_saveexec_b64 s[2:3], s[4:5]
	s_xor_b64 s[2:3], exec, s[2:3]
	s_andn2_saveexec_b64 s[2:3], s[2:3]
	v_or3_b32 v25, v29, v26, v27
	s_or_b64 exec, exec, s[2:3]
	v_add_u32_e32 v4, v25, v28
	v_mov_b64_e32 v[2:3], s[6:7]
	v_mad_i64_i32 v[2:3], s[2:3], v4, s65, v[2:3]
	v_lshl_add_u64 v[2:3], v[2:3], 0, v[0:1]
	global_load_dwordx4 v[72:75], v[2:3], off offset:256
	global_load_dwordx4 v[76:79], v[90:91], off offset:256
	v_ashrrev_i32_e32 v85, 8, v19
	v_and_b32_e32 v2, 31, v19
	v_bfe_u32 v93, v19, 5, 1
	v_lshlrev_b32_e32 v84, 6, v85
	v_or_b32_e32 v3, v84, v2
	v_lshlrev_b32_e32 v88, 4, v93
	v_mad_u64_u32 v[96:97], s[2:3], v3, s70, v[88:89]
	v_lshrrev_b32_e32 v3, 1, v19
	v_and_or_b32 v95, v3, s86, v2
	v_mul_u32_u24_e32 v2, 0x48, v95
	v_and_b32_e32 v3, 3, v18
	v_lshl_add_u32 v97, v2, 1, v88
	v_and_b32_e32 v2, 31, v18
	v_or3_b32 v3, v21, v3, v20
	v_cndmask_b32_e32 v5, v2, v3, vcc
	v_lshl_add_u64 v[2:3], s[6:7], 0, v[0:1]
	v_or_b32_e32 v0, v22, v5
	v_mov_b32_e32 v14, v1
	v_mov_b32_e32 v15, v1
	v_mad_i64_i32 v[98:99], s[2:3], v0, s65, v[2:3]
	v_mad_i64_i32 v[100:101], s[2:3], v4, s65, v[2:3]
	v_mov_b32_e32 v0, v1
	v_mov_b32_e32 v2, v1
	v_mov_b32_e32 v3, v1
	v_mov_b32_e32 v4, v1
	v_mov_b32_e32 v5, v1
	v_mov_b32_e32 v6, v1
	v_mov_b32_e32 v7, v1
	v_mov_b32_e32 v8, v1
	v_mov_b32_e32 v9, v1
	v_mov_b32_e32 v10, v1
	v_mov_b32_e32 v11, v1
	v_mov_b32_e32 v12, v1
	v_mov_b32_e32 v13, v1
	v_mov_b64_e32 v[30:31], v[14:15]
	v_mov_b64_e32 v[46:47], v[14:15]
	s_mov_b32 s4, 0
	v_mov_b64_e32 v[28:29], v[12:13]
	v_mov_b64_e32 v[26:27], v[10:11]
	v_mov_b64_e32 v[24:25], v[8:9]
	v_mov_b64_e32 v[22:23], v[6:7]
	v_mov_b64_e32 v[20:21], v[4:5]
	v_mov_b64_e32 v[18:19], v[2:3]
	v_mov_b64_e32 v[16:17], v[0:1]
	v_mov_b64_e32 v[44:45], v[12:13]
	v_mov_b64_e32 v[42:43], v[10:11]
	v_mov_b64_e32 v[40:41], v[8:9]
	v_mov_b64_e32 v[38:39], v[6:7]
	v_mov_b64_e32 v[36:37], v[4:5]
	v_mov_b64_e32 v[34:35], v[2:3]
	v_mov_b64_e32 v[32:33], v[0:1]
	s_waitcnt lgkmcnt(0)
	s_barrier
